# top-k threshold search: wave-wide integer count summed with a DPP reduction instead of a six-step ds_bpermute butterfly (phases 6 and 14)
# speedup vs baseline: 1.0085x; 1.0085x over previous
.LBB0_733:
	s_lshl_b32 s0, 1, s5
	v_or_b32_e32 v37, s0, v34
	v_cmp_ge_u32_e32 vcc, v7, v37
	s_waitcnt lgkmcnt(0)
	s_barrier
	v_cndmask_b32_e64 v38, 0, 1, vcc
	v_cmp_ge_u32_e32 vcc, v6, v37
	s_nop 1
	v_addc_co_u32_e32 v38, vcc, 0, v38, vcc
	v_cmp_ge_u32_e32 vcc, v8, v37
	s_nop 1
	v_cndmask_b32_e64 v39, 0, 1, vcc
	v_cmp_ge_u32_e32 vcc, v9, v37
	s_nop 1
	v_addc_co_u32_e32 v38, vcc, v38, v39, vcc
	v_cmp_ge_u32_e32 vcc, v2, v37
	s_nop 1
	v_cndmask_b32_e64 v39, 0, 1, vcc
	v_cmp_ge_u32_e32 vcc, v3, v37
	s_nop 1
	v_addc_co_u32_e32 v38, vcc, v38, v39, vcc
	v_cmp_ge_u32_e32 vcc, v4, v37
	s_nop 1
	v_cndmask_b32_e64 v39, 0, 1, vcc
	v_cmp_ge_u32_e32 vcc, v5, v37
	s_nop 1
	v_addc_co_u32_e32 v38, vcc, v38, v39, vcc
	s_nop 1
	v_add_u32_dpp v38, v38, v38 quad_perm:[1,0,3,2] row_mask:0xf bank_mask:0xf
	s_nop 1
	v_add_u32_dpp v38, v38, v38 quad_perm:[2,3,0,1] row_mask:0xf bank_mask:0xf
	s_nop 1
	v_add_u32_dpp v38, v38, v38 row_half_mirror row_mask:0xf bank_mask:0xf
	s_nop 1
	v_add_u32_dpp v38, v38, v38 row_mirror row_mask:0xf bank_mask:0xf
	s_nop 1
	v_add_u32_dpp v38, v38, v38 row_bcast:15 row_mask:0xa bank_mask:0xf
	s_nop 1
	v_add_u32_dpp v38, v38, v38 row_bcast:31 row_mask:0xc bank_mask:0xf
	s_nop 1
	v_readlane_b32 s32, v38, 63
	s_and_saveexec_b64 s[0:1], s[8:9]
	s_cbranch_execz .LBB0_732
	v_mov_b32_e32 v38, s32
	ds_write_b32 v29, v38 offset:16384
	s_branch .LBB0_732

.LBB0_1330:
	s_lshl_b32 s0, 1, s3
	v_or_b32_e32 v37, s0, v34
	v_cmp_ge_u32_e32 vcc, v7, v37
	s_waitcnt lgkmcnt(0)
	s_barrier
	v_cndmask_b32_e64 v38, 0, 1, vcc
	v_cmp_ge_u32_e32 vcc, v6, v37
	s_nop 1
	v_addc_co_u32_e32 v38, vcc, 0, v38, vcc
	v_cmp_ge_u32_e32 vcc, v8, v37
	s_nop 1
	v_cndmask_b32_e64 v39, 0, 1, vcc
	v_cmp_ge_u32_e32 vcc, v9, v37
	s_nop 1
	v_addc_co_u32_e32 v38, vcc, v38, v39, vcc
	v_cmp_ge_u32_e32 vcc, v2, v37
	s_nop 1
	v_cndmask_b32_e64 v39, 0, 1, vcc
	v_cmp_ge_u32_e32 vcc, v3, v37
	s_nop 1
	v_addc_co_u32_e32 v38, vcc, v38, v39, vcc
	v_cmp_ge_u32_e32 vcc, v4, v37
	s_nop 1
	v_cndmask_b32_e64 v39, 0, 1, vcc
	v_cmp_ge_u32_e32 vcc, v5, v37
	s_nop 1
	v_addc_co_u32_e32 v38, vcc, v38, v39, vcc
	s_nop 1
	v_add_u32_dpp v38, v38, v38 quad_perm:[1,0,3,2] row_mask:0xf bank_mask:0xf
	s_nop 1
	v_add_u32_dpp v38, v38, v38 quad_perm:[2,3,0,1] row_mask:0xf bank_mask:0xf
	s_nop 1
	v_add_u32_dpp v38, v38, v38 row_half_mirror row_mask:0xf bank_mask:0xf
	s_nop 1
	v_add_u32_dpp v38, v38, v38 row_mirror row_mask:0xf bank_mask:0xf
	s_nop 1
	v_add_u32_dpp v38, v38, v38 row_bcast:15 row_mask:0xa bank_mask:0xf
	s_nop 1
	v_add_u32_dpp v38, v38, v38 row_bcast:31 row_mask:0xc bank_mask:0xf
	s_nop 1
	v_readlane_b32 s32, v38, 63
	s_and_saveexec_b64 s[0:1], s[8:9]
	s_cbranch_execz .LBB0_1329
	v_mov_b32_e32 v38, s32
	ds_write_b32 v29, v38 offset:16384
	s_branch .LBB0_1329
